# code placement: conv-gate K-loop head at byte phase 4 mod 64 (others 16 / 12)
# speedup vs baseline: 1.0048x; 1.0048x over previous
; #define PG8_STAGE(bufoff, gbase, voff) do { _Pragma("unroll") for (int _i = 0; _i < 2; ++_i) \
;         __builtin_amdgcn_global_load_lds((const unsigned*)((const char*)(gbase) + (voff)[_i]), (LAS unsigned*)(lds + (bufoff) + ldsw + _i * 8192), 16, 0, 0); } while (0)
; #define PG8_LDA(dst, b, h) do { _Pragma("unroll") for (int m = 0; m < 4; ++m) _Pragma("unroll") for (int k = 0; k < 2; ++k) dst[m][k] = *(const LAS bf16x8*)(lds + PG8_SA(b, h) + aoff + m * 2048 + k * 1024); } while (0)
; #define PG8_LDB(dst, b, h) do { _Pragma("unroll") for (int n = 0; n < 2; ++n) _Pragma("unroll") for (int k = 0; k < 2; ++k) dst[n][k] = *(const LAS bf16x8*)(lds + PG8_SB(b, h) + boff + n * 2048 + k * 1024); } while (0)
; #define PG8_MMA(ai, bj, At, Bt) do { __builtin_amdgcn_s_setprio(1); _Pragma("unroll") for (int m = 0; m < 4; ++m) _Pragma("unroll") for (int n = 0; n < 2; ++n) _Pragma("unroll") for (int k = 0; k < 2; ++k) \
;         acc[ai][bj][m][n] = __builtin_amdgcn_mfma_f32_16x16x32_bf16(Bt[n][k], At[m][k], acc[ai][bj][m][n], 0, 0, 0); __builtin_amdgcn_s_setprio(0); } while (0)
; #define PG8_WAIT_V(n) asm volatile("s_waitcnt vmcnt(" #n ")" ::: "memory")
; #define PG8_WAIT_L(n) asm volatile("s_waitcnt lgkmcnt(" #n ")" ::: "memory")
; #define PG8_BAR __builtin_amdgcn_s_barrier()
; #define PG8_SCHED __builtin_amdgcn_sched_barrier(0)
;     ...
;         const bool has_next = S.next(ui + 1, nxt);
;         const char* nA = has_next ? nxt.A : cA; const char* nB = has_next ? nxt.B : cB;
;         for (int t = 0; t < nt; t += 2) {
;             const bool last = (t == nt - 2);
;             const char* a1 = cA + (size_t)(t + 1) * kstep;
;             const char* a2 = last ? nA : cA + (size_t)(t + 2) * kstep; const char* b2 = last ? nB : cB + (size_t)(t + 2) * kstep;
;             const char* a3 = a2 + kstep; const char* b3 = b2 + kstep;
;             PG8_LDB(B0, 0, 0); PG8_LDB(B1, 0, 1); PG8_SCHED; PG8_LDA(At, 0, 0); PG8_STAGE(PG8_SA(1, 1), a1 + hstepA, voffA);
;             PG8_WAIT_V(8); PG8_WAIT_L(0); PG8_BAR; PG8_MMA(0, 0, At, B0); PG8_MMA(0, 1, At, B1); PG8_BAR; PG8_SCHED;
;             PG8_LDA(At, 0, 1); PG8_STAGE(PG8_SB(0, 0), b2, voffB); PG8_STAGE(PG8_SB(0, 1), b2 + hstepB, voffB); PG8_STAGE(PG8_SA(0, 0), a2, voffA);
;             PG8_WAIT_V(8); PG8_WAIT_L(0); PG8_BAR; PG8_MMA(1, 0, At, B0); PG8_MMA(1, 1, At, B1); PG8_BAR; PG8_SCHED;
.LBB0_158:
	s_mov_b64 s[56:57], s[18:19]
	s_mov_b64 s[16:17], s[2:3]
	v_mov_b32_e32 v228, v128
	s_xor_b64 s[2:3], s[36:37], -1
	v_mov_b32_e32 v128, s57
	s_and_b64 s[0:1], s[36:37], exec
	v_cndmask_b32_e64 v132, v189, v128, s[36:37]
	v_mov_b32_e32 v128, s56
	s_mov_b64 s[68:69], s[8:9]
	s_mov_b64 s[54:55], s[40:41]
	s_cselect_b32 s18, s17, s13
	s_cselect_b32 s19, s16, s12
	v_cndmask_b32_e64 v133, v188, v128, s[36:37]
	s_mov_b32 s8, 0
	s_mov_b64 s[0:1], 0x100
	v_mov_b64_e32 v[128:129], v[202:203]
	v_mov_b64_e32 v[130:131], v[200:201]
	s_nop 0
	s_nop 0
	s_nop 0
	s_nop 0
	s_nop 0
	s_nop 0
	s_nop 0
	s_nop 0
.LBB0_159:
	s_add_i32 s38, s8, 2
	s_add_u32 s26, s12, s0
	s_addc_u32 s9, s13, s1
	s_add_i32 s27, 0, 0x10000
	s_cmp_eq_u32 s63, s8
	s_cselect_b32 s9, s18, s9
	s_cselect_b32 s8, s19, s26
	s_cselect_b64 vcc, -1, 0
	s_add_i32 s26, 0, 0x14000
	v_lshl_add_u64 v[150:151], v[188:189], 0, s[0:1]
	v_add_u32_e32 v146, s27, v226
	v_add_u32_e32 v162, s26, v226
	ds_read_b128 v[134:137], v146
	ds_read_b128 v[138:141], v146 offset:1024
	ds_read_b128 v[142:145], v146 offset:2048
	ds_read_b128 v[146:149], v146 offset:3072
	v_cndmask_b32_e32 v205, v151, v132, vcc
	v_cndmask_b32_e32 v204, v150, v133, vcc
	ds_read_b128 v[150:153], v162
	ds_read_b128 v[154:157], v162 offset:1024
	ds_read_b128 v[158:161], v162 offset:2048
	ds_read_b128 v[162:165], v162 offset:3072
	v_lshl_add_u64 v[212:213], s[12:13], 0, v[130:131]
	s_add_i32 m0, s20, 0xc000
	ds_read_b128 v[166:169], v227
	ds_read_b128 v[170:173], v227 offset:1024
	ds_read_b128 v[174:177], v227 offset:2048
	ds_read_b128 v[178:181], v227 offset:3072
	ds_read_b128 v[230:233], v227 offset:4096
	ds_read_b128 v[234:237], v227 offset:5120
	ds_read_b128 v[238:241], v227 offset:6144
	ds_read_b128 v[242:245], v227 offset:7168
	global_load_lds_dwordx4 v[212:213], off
	v_lshl_add_u64 v[212:213], s[12:13], 0, v[128:129]
	s_add_i32 m0, s20, 0xe000
	s_nop 0
	global_load_lds_dwordx4 v[212:213], off
	s_waitcnt vmcnt(8)
	s_waitcnt lgkmcnt(0)
	s_barrier
	s_setprio 1
	s_waitcnt lgkmcnt(0)
	v_mfma_f32_16x16x32_bf16 v[124:127], v[134:137], v[166:169], v[124:127]
	v_mfma_f32_16x16x32_bf16 v[0:3], v[142:145], v[166:169], v[0:3]
	v_mfma_f32_16x16x32_bf16 v[120:123], v[134:137], v[174:177], v[120:123]
	v_mfma_f32_16x16x32_bf16 v[116:119], v[142:145], v[174:177], v[116:119]
	v_mfma_f32_16x16x32_bf16 v[112:115], v[134:137], v[230:233], v[112:115]
	v_mfma_f32_16x16x32_bf16 v[108:111], v[142:145], v[230:233], v[108:111]
	v_mfma_f32_16x16x32_bf16 v[104:107], v[134:137], v[238:241], v[104:107]
	v_mfma_f32_16x16x32_bf16 v[4:7], v[142:145], v[238:241], v[4:7]
	v_mfma_f32_16x16x32_bf16 v[124:127], v[138:141], v[170:173], v[124:127]
	v_mfma_f32_16x16x32_bf16 v[0:3], v[146:149], v[170:173], v[0:3]
	v_mfma_f32_16x16x32_bf16 v[120:123], v[138:141], v[178:181], v[120:123]
	v_mfma_f32_16x16x32_bf16 v[116:119], v[146:149], v[178:181], v[116:119]
	v_mfma_f32_16x16x32_bf16 v[112:115], v[138:141], v[234:237], v[112:115]
	v_mfma_f32_16x16x32_bf16 v[108:111], v[146:149], v[234:237], v[108:111]
	v_mfma_f32_16x16x32_bf16 v[104:107], v[138:141], v[242:245], v[104:107]
	v_mfma_f32_16x16x32_bf16 v[4:7], v[146:149], v[242:245], v[4:7]
	s_setprio 0
	s_setprio 1
	v_mfma_f32_16x16x32_bf16 v[100:103], v[150:153], v[166:169], v[100:103]
	v_mfma_f32_16x16x32_bf16 v[96:99], v[158:161], v[166:169], v[96:99]
	v_mfma_f32_16x16x32_bf16 v[92:95], v[150:153], v[174:177], v[92:95]
	v_mfma_f32_16x16x32_bf16 v[88:91], v[158:161], v[174:177], v[88:91]
	v_mfma_f32_16x16x32_bf16 v[84:87], v[150:153], v[230:233], v[84:87]
	v_mfma_f32_16x16x32_bf16 v[80:83], v[158:161], v[230:233], v[80:83]
	v_mfma_f32_16x16x32_bf16 v[76:79], v[150:153], v[238:241], v[76:79]
	v_mfma_f32_16x16x32_bf16 v[72:75], v[158:161], v[238:241], v[72:75]
	v_mfma_f32_16x16x32_bf16 v[100:103], v[154:157], v[170:173], v[100:103]
	v_mfma_f32_16x16x32_bf16 v[96:99], v[162:165], v[170:173], v[96:99]
	v_mfma_f32_16x16x32_bf16 v[92:95], v[154:157], v[178:181], v[92:95]
	v_mfma_f32_16x16x32_bf16 v[88:91], v[162:165], v[178:181], v[88:91]
	v_mfma_f32_16x16x32_bf16 v[84:87], v[154:157], v[234:237], v[84:87]
	v_mfma_f32_16x16x32_bf16 v[80:83], v[162:165], v[234:237], v[80:83]
	v_mfma_f32_16x16x32_bf16 v[76:79], v[154:157], v[242:245], v[76:79]
	v_mfma_f32_16x16x32_bf16 v[72:75], v[162:165], v[242:245], v[72:75]
	s_setprio 0
	s_barrier
	s_add_i32 s27, s27, s11
	v_lshl_add_u64 v[212:213], v[204:205], 0, v[192:193]
	s_mov_b32 m0, s27
	ds_read_b128 v[166:169], v227 offset:16384
	ds_read_b128 v[170:173], v227 offset:17408
	ds_read_b128 v[174:177], v227 offset:18432
	ds_read_b128 v[178:181], v227 offset:19456
	ds_read_b128 v[230:233], v227 offset:20480
	ds_read_b128 v[234:237], v227 offset:21504
	ds_read_b128 v[238:241], v227 offset:22528
	ds_read_b128 v[242:245], v227 offset:23552
	global_load_lds_dwordx4 v[212:213], off
	v_lshl_add_u64 v[218:219], v[204:205], 0, v[196:197]
	s_add_i32 m0, s27, 0x2000
	v_lshl_add_u64 v[204:205], v[204:205], 0, v[198:199]
	s_add_i32 s26, s26, s11
	global_load_lds_dwordx4 v[218:219], off
	v_lshl_add_u64 v[246:247], v[204:205], 0, v[192:193]
	s_mov_b32 m0, s26
	v_lshl_add_u64 v[204:205], v[204:205], 0, v[196:197]
	global_load_lds_dwordx4 v[246:247], off
	s_add_i32 m0, s26, 0x2000
	v_lshl_add_u64 v[248:249], s[8:9], 0, v[190:191]
	global_load_lds_dwordx4 v[204:205], off
	s_mov_b32 m0, s20
	v_lshl_add_u64 v[250:251], s[8:9], 0, v[194:195]
	global_load_lds_dwordx4 v[248:249], off
	s_mov_b32 m0, s48
	s_nop 0
	global_load_lds_dwordx4 v[250:251], off
	s_waitcnt vmcnt(8)
	s_waitcnt lgkmcnt(0)
	s_barrier
; #define PG8_STAGE(bufoff, gbase, voff) do { _Pragma("unroll") for (int _i = 0; _i < 2; ++_i) \
;         __builtin_amdgcn_global_load_lds((const unsigned*)((const char*)(gbase) + (voff)[_i]), (LAS unsigned*)(lds + (bufoff) + ldsw + _i * 8192), 16, 0, 0); } while (0)
; #define PG8_LDA(dst, b, h) do { _Pragma("unroll") for (int m = 0; m < 4; ++m) _Pragma("unroll") for (int k = 0; k < 2; ++k) dst[m][k] = *(const LAS bf16x8*)(lds + PG8_SA(b, h) + aoff + m * 2048 + k * 1024); } while (0)
; #define PG8_LDB(dst, b, h) do { _Pragma("unroll") for (int n = 0; n < 2; ++n) _Pragma("unroll") for (int k = 0; k < 2; ++k) dst[n][k] = *(const LAS bf16x8*)(lds + PG8_SB(b, h) + boff + n * 2048 + k * 1024); } while (0)
; #define PG8_MMA(ai, bj, At, Bt) do { __builtin_amdgcn_s_setprio(1); _Pragma("unroll") for (int m = 0; m < 4; ++m) _Pragma("unroll") for (int n = 0; n < 2; ++n) _Pragma("unroll") for (int k = 0; k < 2; ++k) \
;         acc[ai][bj][m][n] = __builtin_amdgcn_mfma_f32_16x16x32_bf16(Bt[n][k], At[m][k], acc[ai][bj][m][n], 0, 0, 0); __builtin_amdgcn_s_setprio(0); } while (0)
; #define PG8_WAIT_V(n) asm volatile("s_waitcnt vmcnt(" #n ")" ::: "memory")
; #define PG8_WAIT_L(n) asm volatile("s_waitcnt lgkmcnt(" #n ")" ::: "memory")
; #define PG8_BAR __builtin_amdgcn_s_barrier()
; #define PG8_SCHED __builtin_amdgcn_sched_barrier(0)
;     ...
;             PG8_WAIT_V(8); PG8_WAIT_L(0); PG8_BAR; PG8_MMA(1, 0, At, B0); PG8_MMA(1, 1, At, B1); PG8_BAR; PG8_SCHED;
;             PG8_LDB(B0, 1, 0); PG8_LDB(B1, 1, 1); PG8_SCHED; PG8_LDA(At, 1, 0); PG8_STAGE(PG8_SA(0, 1), a2 + hstepA, voffA);
;             PG8_WAIT_V(8); PG8_WAIT_L(0); PG8_BAR; PG8_MMA(0, 0, At, B0); PG8_MMA(0, 1, At, B1); PG8_BAR; PG8_SCHED;
	s_setprio 1
	s_waitcnt lgkmcnt(0)
	v_mfma_f32_16x16x32_bf16 v[68:71], v[134:137], v[166:169], v[68:71]
	v_mfma_f32_16x16x32_bf16 v[8:11], v[142:145], v[166:169], v[8:11]
	v_mfma_f32_16x16x32_bf16 v[64:67], v[134:137], v[174:177], v[64:67]
	v_mfma_f32_16x16x32_bf16 v[60:63], v[142:145], v[174:177], v[60:63]
	v_mfma_f32_16x16x32_bf16 v[56:59], v[134:137], v[230:233], v[56:59]
	v_mfma_f32_16x16x32_bf16 v[52:55], v[142:145], v[230:233], v[52:55]
	v_mfma_f32_16x16x32_bf16 v[48:51], v[134:137], v[238:241], v[48:51]
	v_mfma_f32_16x16x32_bf16 v[12:15], v[142:145], v[238:241], v[12:15]
	v_mfma_f32_16x16x32_bf16 v[68:71], v[138:141], v[170:173], v[68:71]
	v_mfma_f32_16x16x32_bf16 v[8:11], v[146:149], v[170:173], v[8:11]
	v_mfma_f32_16x16x32_bf16 v[64:67], v[138:141], v[178:181], v[64:67]
	v_mfma_f32_16x16x32_bf16 v[60:63], v[146:149], v[178:181], v[60:63]
	v_mfma_f32_16x16x32_bf16 v[56:59], v[138:141], v[234:237], v[56:59]
	v_mfma_f32_16x16x32_bf16 v[52:55], v[146:149], v[234:237], v[52:55]
	v_mfma_f32_16x16x32_bf16 v[48:51], v[138:141], v[242:245], v[48:51]
	v_mfma_f32_16x16x32_bf16 v[12:15], v[146:149], v[242:245], v[12:15]
	s_setprio 0
	s_setprio 1
	v_mfma_f32_16x16x32_bf16 v[44:47], v[150:153], v[166:169], v[44:47]
	v_mfma_f32_16x16x32_bf16 v[40:43], v[158:161], v[166:169], v[40:43]
	v_mfma_f32_16x16x32_bf16 v[36:39], v[150:153], v[174:177], v[36:39]
	v_mfma_f32_16x16x32_bf16 v[32:35], v[158:161], v[174:177], v[32:35]
	v_mfma_f32_16x16x32_bf16 v[28:31], v[150:153], v[230:233], v[28:31]
	v_mfma_f32_16x16x32_bf16 v[24:27], v[158:161], v[230:233], v[24:27]
	v_mfma_f32_16x16x32_bf16 v[20:23], v[150:153], v[238:241], v[20:23]
	v_mfma_f32_16x16x32_bf16 v[16:19], v[158:161], v[238:241], v[16:19]
	v_mfma_f32_16x16x32_bf16 v[44:47], v[154:157], v[170:173], v[44:47]
	v_mfma_f32_16x16x32_bf16 v[40:43], v[162:165], v[170:173], v[40:43]
	v_mfma_f32_16x16x32_bf16 v[36:39], v[154:157], v[178:181], v[36:39]
	v_mfma_f32_16x16x32_bf16 v[32:35], v[162:165], v[178:181], v[32:35]
	v_mfma_f32_16x16x32_bf16 v[28:31], v[154:157], v[234:237], v[28:31]
	v_mfma_f32_16x16x32_bf16 v[24:27], v[162:165], v[234:237], v[24:27]
	v_mfma_f32_16x16x32_bf16 v[20:23], v[154:157], v[242:245], v[20:23]
	v_mfma_f32_16x16x32_bf16 v[16:19], v[162:165], v[242:245], v[16:19]
	s_setprio 0
	s_barrier
	s_add_i32 s26, 0, 0x18000
	s_add_i32 s27, 0, 0x1c000
	v_add_u32_e32 v146, s26, v226
	v_add_u32_e32 v162, s27, v226
	ds_read_b128 v[134:137], v146
	ds_read_b128 v[138:141], v146 offset:1024
	ds_read_b128 v[142:145], v146 offset:2048
	ds_read_b128 v[146:149], v146 offset:3072
	ds_read_b128 v[150:153], v162
	ds_read_b128 v[154:157], v162 offset:1024
	ds_read_b128 v[158:161], v162 offset:2048
	ds_read_b128 v[162:165], v162 offset:3072
	s_add_u32 s8, s8, s10
	s_addc_u32 s9, s9, 0
	s_mov_b32 m0, s51
	v_lshl_add_u64 v[214:215], s[8:9], 0, v[190:191]
	ds_read_b128 v[166:169], v227 offset:32768
	ds_read_b128 v[170:173], v227 offset:33792
	ds_read_b128 v[174:177], v227 offset:34816
	ds_read_b128 v[178:181], v227 offset:35840
	ds_read_b128 v[230:233], v227 offset:36864
	ds_read_b128 v[234:237], v227 offset:37888
	ds_read_b128 v[238:241], v227 offset:38912
	ds_read_b128 v[242:245], v227 offset:39936
	global_load_lds_dwordx4 v[214:215], off
	v_lshl_add_u64 v[214:215], s[8:9], 0, v[194:195]
	s_mov_b32 m0, s62
	s_nop 0
	global_load_lds_dwordx4 v[214:215], off
	s_waitcnt vmcnt(8)
	s_waitcnt lgkmcnt(0)
	s_barrier
	s_setprio 1
	s_waitcnt lgkmcnt(0)
	v_mfma_f32_16x16x32_bf16 v[124:127], v[134:137], v[166:169], v[124:127]
	v_mfma_f32_16x16x32_bf16 v[0:3], v[142:145], v[166:169], v[0:3]
	v_mfma_f32_16x16x32_bf16 v[120:123], v[134:137], v[174:177], v[120:123]
	v_mfma_f32_16x16x32_bf16 v[116:119], v[142:145], v[174:177], v[116:119]
	v_mfma_f32_16x16x32_bf16 v[112:115], v[134:137], v[230:233], v[112:115]
	v_mfma_f32_16x16x32_bf16 v[108:111], v[142:145], v[230:233], v[108:111]
	v_mfma_f32_16x16x32_bf16 v[104:107], v[134:137], v[238:241], v[104:107]
	v_mfma_f32_16x16x32_bf16 v[4:7], v[142:145], v[238:241], v[4:7]
	v_mfma_f32_16x16x32_bf16 v[124:127], v[138:141], v[170:173], v[124:127]
	v_mfma_f32_16x16x32_bf16 v[0:3], v[146:149], v[170:173], v[0:3]
	v_mfma_f32_16x16x32_bf16 v[120:123], v[138:141], v[178:181], v[120:123]
	v_mfma_f32_16x16x32_bf16 v[116:119], v[146:149], v[178:181], v[116:119]
	v_mfma_f32_16x16x32_bf16 v[112:115], v[138:141], v[234:237], v[112:115]
	v_mfma_f32_16x16x32_bf16 v[108:111], v[146:149], v[234:237], v[108:111]
	v_mfma_f32_16x16x32_bf16 v[104:107], v[138:141], v[242:245], v[104:107]
	v_mfma_f32_16x16x32_bf16 v[4:7], v[146:149], v[242:245], v[4:7]
	s_setprio 0
	s_setprio 1
	v_mfma_f32_16x16x32_bf16 v[100:103], v[150:153], v[166:169], v[100:103]
	v_mfma_f32_16x16x32_bf16 v[96:99], v[158:161], v[166:169], v[96:99]
	v_mfma_f32_16x16x32_bf16 v[92:95], v[150:153], v[174:177], v[92:95]
	v_mfma_f32_16x16x32_bf16 v[88:91], v[158:161], v[174:177], v[88:91]
	v_mfma_f32_16x16x32_bf16 v[84:87], v[150:153], v[230:233], v[84:87]
	v_mfma_f32_16x16x32_bf16 v[80:83], v[158:161], v[230:233], v[80:83]
	v_mfma_f32_16x16x32_bf16 v[76:79], v[150:153], v[238:241], v[76:79]
	v_mfma_f32_16x16x32_bf16 v[72:75], v[158:161], v[238:241], v[72:75]
	v_mfma_f32_16x16x32_bf16 v[100:103], v[154:157], v[170:173], v[100:103]
	v_mfma_f32_16x16x32_bf16 v[96:99], v[162:165], v[170:173], v[96:99]
	v_mfma_f32_16x16x32_bf16 v[92:95], v[154:157], v[178:181], v[92:95]
	v_mfma_f32_16x16x32_bf16 v[88:91], v[162:165], v[178:181], v[88:91]
	v_mfma_f32_16x16x32_bf16 v[84:87], v[154:157], v[234:237], v[84:87]
	v_mfma_f32_16x16x32_bf16 v[80:83], v[162:165], v[234:237], v[80:83]
	v_mfma_f32_16x16x32_bf16 v[76:79], v[154:157], v[242:245], v[76:79]
	v_mfma_f32_16x16x32_bf16 v[72:75], v[162:165], v[242:245], v[72:75]
	s_setprio 0
	s_barrier
; #define PG8_STAGE(bufoff, gbase, voff) do { _Pragma("unroll") for (int _i = 0; _i < 2; ++_i) \
;         __builtin_amdgcn_global_load_lds((const unsigned*)((const char*)(gbase) + (voff)[_i]), (LAS unsigned*)(lds + (bufoff) + ldsw + _i * 8192), 16, 0, 0); } while (0)
; #define PG8_LDA(dst, b, h) do { _Pragma("unroll") for (int m = 0; m < 4; ++m) _Pragma("unroll") for (int k = 0; k < 2; ++k) dst[m][k] = *(const LAS bf16x8*)(lds + PG8_SA(b, h) + aoff + m * 2048 + k * 1024); } while (0)
; #define PG8_MMA(ai, bj, At, Bt) do { __builtin_amdgcn_s_setprio(1); _Pragma("unroll") for (int m = 0; m < 4; ++m) _Pragma("unroll") for (int n = 0; n < 2; ++n) _Pragma("unroll") for (int k = 0; k < 2; ++k) \
;         acc[ai][bj][m][n] = __builtin_amdgcn_mfma_f32_16x16x32_bf16(Bt[n][k], At[m][k], acc[ai][bj][m][n], 0, 0, 0); __builtin_amdgcn_s_setprio(0); } while (0)
; #define PG8_WAIT_V(n) asm volatile("s_waitcnt vmcnt(" #n ")" ::: "memory")
; #define PG8_WAIT_L(n) asm volatile("s_waitcnt lgkmcnt(" #n ")" ::: "memory")
; #define PG8_BAR __builtin_amdgcn_s_barrier()
; #define PG8_SCHED __builtin_amdgcn_sched_barrier(0)
;     ...
;             PG8_WAIT_V(8); PG8_WAIT_L(0); PG8_BAR; PG8_MMA(0, 0, At, B0); PG8_MMA(0, 1, At, B1); PG8_BAR; PG8_SCHED;
;             PG8_LDA(At, 1, 1); PG8_STAGE(PG8_SB(1, 0), b3, voffB); PG8_STAGE(PG8_SB(1, 1), b3 + hstepB, voffB); PG8_STAGE(PG8_SA(1, 0), a3, voffA);
;             PG8_WAIT_V(8); PG8_WAIT_L(0); PG8_BAR; PG8_MMA(1, 0, At, B0); PG8_MMA(1, 1, At, B1); PG8_BAR; PG8_SCHED;
;         }
;         if (wr == 0) PG8_BAR;
	s_add_i32 s8, s26, s11
	v_lshl_add_u64 v[212:213], v[212:213], 0, s[70:71]
	s_mov_b32 m0, s8
	ds_read_b128 v[166:169], v227 offset:49152
	ds_read_b128 v[170:173], v227 offset:50176
	ds_read_b128 v[174:177], v227 offset:51200
	ds_read_b128 v[178:181], v227 offset:52224
	ds_read_b128 v[230:233], v227 offset:53248
	ds_read_b128 v[234:237], v227 offset:54272
	ds_read_b128 v[238:241], v227 offset:55296
	ds_read_b128 v[242:245], v227 offset:56320
	global_load_lds_dwordx4 v[212:213], off
	v_lshl_add_u64 v[212:213], v[218:219], 0, s[70:71]
	s_add_i32 m0, s8, 0x2000
	s_add_i32 s8, s27, s11
	global_load_lds_dwordx4 v[212:213], off
	v_lshl_add_u64 v[212:213], v[246:247], 0, s[70:71]
	s_mov_b32 m0, s8
	v_lshl_add_u64 v[204:205], v[204:205], 0, s[70:71]
	global_load_lds_dwordx4 v[212:213], off
	s_add_i32 m0, s8, 0x2000
	s_nop 0
	global_load_lds_dwordx4 v[204:205], off
	v_lshl_add_u64 v[204:205], v[248:249], 0, s[70:71]
	s_mov_b32 m0, s65
	s_nop 0
	global_load_lds_dwordx4 v[204:205], off
	v_lshl_add_u64 v[204:205], v[250:251], 0, s[70:71]
	s_mov_b32 m0, s49
	s_nop 0
	global_load_lds_dwordx4 v[204:205], off
	s_waitcnt vmcnt(8)
	s_waitcnt lgkmcnt(0)
	s_barrier
	s_setprio 1
	s_waitcnt lgkmcnt(0)
	v_mfma_f32_16x16x32_bf16 v[68:71], v[134:137], v[166:169], v[68:71]
	v_mfma_f32_16x16x32_bf16 v[8:11], v[142:145], v[166:169], v[8:11]
	v_mfma_f32_16x16x32_bf16 v[64:67], v[134:137], v[174:177], v[64:67]
	v_mfma_f32_16x16x32_bf16 v[60:63], v[142:145], v[174:177], v[60:63]
	v_mfma_f32_16x16x32_bf16 v[56:59], v[134:137], v[230:233], v[56:59]
	v_mfma_f32_16x16x32_bf16 v[52:55], v[142:145], v[230:233], v[52:55]
	v_mfma_f32_16x16x32_bf16 v[48:51], v[134:137], v[238:241], v[48:51]
	v_mfma_f32_16x16x32_bf16 v[12:15], v[142:145], v[238:241], v[12:15]
	v_mfma_f32_16x16x32_bf16 v[68:71], v[138:141], v[170:173], v[68:71]
	v_mfma_f32_16x16x32_bf16 v[8:11], v[146:149], v[170:173], v[8:11]
	v_mfma_f32_16x16x32_bf16 v[64:67], v[138:141], v[178:181], v[64:67]
	v_mfma_f32_16x16x32_bf16 v[60:63], v[146:149], v[178:181], v[60:63]
	v_mfma_f32_16x16x32_bf16 v[56:59], v[138:141], v[234:237], v[56:59]
	v_mfma_f32_16x16x32_bf16 v[52:55], v[146:149], v[234:237], v[52:55]
	v_mfma_f32_16x16x32_bf16 v[48:51], v[138:141], v[242:245], v[48:51]
	v_mfma_f32_16x16x32_bf16 v[12:15], v[146:149], v[242:245], v[12:15]
	s_setprio 0
	s_setprio 1
	v_mfma_f32_16x16x32_bf16 v[44:47], v[150:153], v[166:169], v[44:47]
	v_mfma_f32_16x16x32_bf16 v[40:43], v[158:161], v[166:169], v[40:43]
	v_mfma_f32_16x16x32_bf16 v[36:39], v[150:153], v[174:177], v[36:39]
	v_mfma_f32_16x16x32_bf16 v[32:35], v[158:161], v[174:177], v[32:35]
	v_mfma_f32_16x16x32_bf16 v[28:31], v[150:153], v[230:233], v[28:31]
	v_mfma_f32_16x16x32_bf16 v[24:27], v[158:161], v[230:233], v[24:27]
	v_mfma_f32_16x16x32_bf16 v[20:23], v[150:153], v[238:241], v[20:23]
	v_mfma_f32_16x16x32_bf16 v[16:19], v[158:161], v[238:241], v[16:19]
	v_mfma_f32_16x16x32_bf16 v[44:47], v[154:157], v[170:173], v[44:47]
	v_mfma_f32_16x16x32_bf16 v[40:43], v[162:165], v[170:173], v[40:43]
	v_mfma_f32_16x16x32_bf16 v[36:39], v[154:157], v[178:181], v[36:39]
	v_mfma_f32_16x16x32_bf16 v[32:35], v[162:165], v[178:181], v[32:35]
	v_mfma_f32_16x16x32_bf16 v[28:31], v[154:157], v[234:237], v[28:31]
	v_mfma_f32_16x16x32_bf16 v[24:27], v[162:165], v[234:237], v[24:27]
	v_mfma_f32_16x16x32_bf16 v[20:23], v[154:157], v[242:245], v[20:23]
	v_mfma_f32_16x16x32_bf16 v[16:19], v[162:165], v[242:245], v[16:19]
	s_setprio 0
	s_barrier
	s_add_u32 s0, s0, 0x100
	s_addc_u32 s1, s1, 0
	v_lshl_add_u64 v[130:131], v[130:131], 0, s[94:95]
	v_lshl_add_u64 v[128:129], v[128:129], 0, s[94:95]
	s_cmp_ge_u32 s38, s52
	s_mov_b32 s8, s38
	s_cbranch_scc0 .LBB0_159
	v_readlane_b32 s0, v254, 50
	v_readlane_b32 s1, v254, 51
	s_and_b64 vcc, exec, s[0:1]
	s_movk_i32 s67, 0xfe
	s_cbranch_vccz .LBB0_162
	s_barrier

;     ...
;         const bool has_next = S.next(ui + 1, nxt);
;         const char* nA = has_next ? nxt.A : cA; const char* nB = has_next ? nxt.B : cB;
;         for (int t = 0; t < nt; t += 2) {
;             const bool last = (t == nt - 2);
;             const char* a1 = cA + (size_t)(t + 1) * kstep;
;             const char* a2 = last ? nA : cA + (size_t)(t + 2) * kstep; const char* b2 = last ? nB : cB + (size_t)(t + 2) * kstep;
.LBB0_317:
	s_mov_b64 s[54:55], s[68:69]
	v_mov_b32_e32 v189, v128
	s_xor_b64 s[66:67], s[64:65], -1
	v_mov_b32_e32 v128, s55
	s_mov_b64 s[36:37], s[38:39]
	s_and_b64 s[0:1], s[64:65], exec
	v_cndmask_b32_e64 v132, v161, v128, s[64:65]
	v_mov_b32_e32 v128, s54
	s_mov_b64 s[6:7], s[56:57]
	s_mov_b64 s[14:15], s[58:59]
	s_mov_b32 s26, s19
	s_cselect_b32 s13, s37, s3
	s_cselect_b32 s56, s36, s2
	v_cndmask_b32_e64 v133, v160, v128, s[64:65]
	s_mov_b32 s38, 0
	s_mov_b64 s[0:1], 0x100
	v_mov_b64_e32 v[128:129], v[172:173]
	v_mov_b64_e32 v[130:131], v[170:171]
	s_nop 0
	s_nop 0
	s_nop 0
	s_nop 0
	s_nop 0
	s_nop 0
	s_nop 0
	s_nop 0
